# v1 plus gemm3 load segments rewritten: LDS-DMA m0 set by SALU from one per-wave base, saddr-form global_load_lds (no VALU address math)
# speedup vs baseline: 1.0005x; 1.0005x over previous
; #define WAIT_V(n) asm volatile("s_waitcnt vmcnt(" #n ")" ::: "memory")
; #define WAIT_L(n) asm volatile("s_waitcnt lgkmcnt(" #n ")" ::: "memory")
; #define BAR __builtin_amdgcn_s_barrier()
; #define SCHED __builtin_amdgcn_sched_barrier(0)
; #define STG_A(b, h, ptr) do { const char* _g = (ptr) + (h) * ahalf; LAS unsigned char* _l = lw + ((b) * 2 + (h)) * 16384; GLDS(_g + voa0, _l); GLDS(_g + voa1, _l + 8192); } while (0)
; #define STG_B(b, h, ptr) do { const char* _g = (ptr) + (h) * bhalf; LAS unsigned char* _l = lw + 65536 + ((b) * 2 + (h)) * 16384; GLDS(_g + vob0, _l); GLDS(_g + vob1, _l + 8192); } while (0)
; #define LDA(dst, b, h) _Pragma("unroll") for (int m = 0; m < 4; ++m) _Pragma("unroll") for (int k = 0; k < 2; ++k) dst[m][k] = *(const LAS bf16x8*)(la + ((b) * 2 + (h)) * 16384 + m * 2048 + k * 1024)
; #define LDB(dst, b, h) _Pragma("unroll") for (int n = 0; n < 2; ++n) _Pragma("unroll") for (int k = 0; k < 2; ++k) dst[n][k] = *(const LAS bf16x8*)(lb + ((b) * 2 + (h)) * 16384 + n * 2048 + k * 1024)
; template <int BMODE, class Epi, class TileFn>
; DEV void gemm_loop(LAS unsigned char* lds, const bf16_t* __restrict__ A, int lda, const bf16_t* __restrict__ B, int ldb, int K, const Epi& epi, int t0, int tstep, int tend, const TileFn& tf) {
;     ...
;         int nrow = brow, ncol = bcol;
;         if (has_next) tf(tt + tstep, nrow, ncol);
;         const char* nA = (const char*)(A + (size_t)nrow * lda);
;         const char* nB = BMODE == 0 ? (const char*)(B + (size_t)ncol * ldb) : (const char*)(B + (size_t)ncol * 8);
;         for (int t = 0; t < nt; t += 2) {
;             const bool last = (t == nt - 2);
;             const char* a1 = cA + (size_t)(t + 1) * 128;
;             const char* a2 = last ? nA : cA + (size_t)(t + 2) * 128;
;             const char* b2 = last ? nB : cB + (size_t)(t + 2) * bks;
;             const char* a3 = a2 + 128; const char* b3 = b2 + bks;
;             LDB(B0, 0, 0); LDB(B1, 0, 1); SCHED; LDA(At, 0, 0); STG_A(1, 1, a1);
;             WAIT_V(8); WAIT_L(0); BAR; MMA(0, 0, At, B0); MMA(0, 1, At, B1); BAR; SCHED;
;             LDA(At, 0, 1); STG_B(0, 0, b2); STG_B(0, 1, b2); STG_A(0, 0, a2);
;             WAIT_V(8); WAIT_L(0); BAR; MMA(1, 0, At, B0); MMA(1, 1, At, B1); BAR; SCHED;
.LBB0_1337:
	v_readfirstlane_b32 s100, v141
	s_ashr_i32 s53, s52, 31
	s_lshl_b64 s[82:83], s[52:53], 11
	s_add_u32 s30, s72, s82
	s_addc_u32 s50, s73, s83
	s_ashr_i32 s81, s80, 31
	s_lshl_b64 s[40:41], s[80:81], 11
	s_add_u32 s53, s48, s40
	s_addc_u32 s74, s49, s41
	s_add_u32 s75, s66, s36
	s_addc_u32 s81, s67, s37
	v_readlane_b32 s31, v254, 63
	s_add_u32 s92, s31, s8
	v_readlane_b32 s8, v250, 0
	v_lshl_add_u64 v[136:137], v[132:133], 0, s[36:37]
	v_lshl_add_u64 v[138:139], v[134:135], 0, s[36:37]
	s_addc_u32 s93, s8, s9
	s_mov_b32 s94, -2
	s_mov_b64 s[36:37], 0
	ds_read_b128 v[158:161], v156
	ds_read_b128 v[162:165], v156 offset:1024
	ds_read_b128 v[166:169], v156 offset:2048
	ds_read_b128 v[170:173], v156 offset:3072
	ds_read_b128 v[174:177], v156 offset:16384
	ds_read_b128 v[178:181], v156 offset:17408
	ds_read_b128 v[182:185], v156 offset:18432
	ds_read_b128 v[196:199], v156 offset:19456
	s_add_u32 s8, s75, s36
	s_addc_u32 s9, s81, s37
	s_add_u32 s8, s8, 0x62e6100
	s_addc_u32 s9, s9, 0
	s_add_u32 s31, s92, s36
	s_addc_u32 s95, s93, s37
	s_cmpk_eq_i32 s36, 0x700
	s_cselect_b32 s55, s50, s9
	s_cselect_b32 s54, s30, s8
	s_cselect_b32 s9, s74, s95
	s_cselect_b32 s8, s53, s31
	v_lshl_add_u64 v[186:187], v[136:137], 0, s[36:37]
	v_lshl_add_u64 v[204:205], v[138:139], 0, s[36:37]
	s_add_u32 m0, s100, 0xc000
	ds_read_b128 v[200:203], v157
	ds_read_b128 v[212:215], v157 offset:1024
	ds_read_b128 v[216:219], v157 offset:2048
	ds_read_b128 v[220:223], v157 offset:3072
	ds_read_b128 v[224:227], v157 offset:4096
	ds_read_b128 v[228:231], v157 offset:5120
	ds_read_b128 v[232:235], v157 offset:6144
	ds_read_b128 v[236:239], v157 offset:7168
	global_load_lds_dwordx4 v[186:187], off
	s_add_u32 m0, s100, 0xe000
	s_nop 0
	global_load_lds_dwordx4 v[204:205], off
	s_waitcnt vmcnt(8)
	s_waitcnt lgkmcnt(0)
	s_barrier
	s_setprio 1
	s_waitcnt lgkmcnt(0)
	v_mfma_f32_16x16x32_bf16 v[124:127], v[158:161], v[200:203], 0
	v_mfma_f32_16x16x32_bf16 v[120:123], v[166:169], v[200:203], 0
	v_mfma_f32_16x16x32_bf16 v[104:107], v[158:161], v[216:219], 0
	v_mfma_f32_16x16x32_bf16 v[108:111], v[166:169], v[216:219], 0
	v_mfma_f32_16x16x32_bf16 v[92:95], v[158:161], v[224:227], 0
	v_mfma_f32_16x16x32_bf16 v[88:91], v[166:169], v[224:227], 0
	v_mfma_f32_16x16x32_bf16 v[72:75], v[158:161], v[232:235], 0
	v_mfma_f32_16x16x32_bf16 v[76:79], v[166:169], v[232:235], 0
	v_mfma_f32_16x16x32_bf16 v[124:127], v[162:165], v[212:215], v[124:127]
	v_mfma_f32_16x16x32_bf16 v[120:123], v[170:173], v[212:215], v[120:123]
	v_mfma_f32_16x16x32_bf16 v[104:107], v[162:165], v[220:223], v[104:107]
	v_mfma_f32_16x16x32_bf16 v[108:111], v[170:173], v[220:223], v[108:111]
	v_mfma_f32_16x16x32_bf16 v[92:95], v[162:165], v[228:231], v[92:95]
	v_mfma_f32_16x16x32_bf16 v[88:91], v[170:173], v[228:231], v[88:91]
	v_mfma_f32_16x16x32_bf16 v[72:75], v[162:165], v[236:239], v[72:75]
	v_mfma_f32_16x16x32_bf16 v[76:79], v[170:173], v[236:239], v[76:79]
	s_setprio 0
	s_setprio 1
	v_mfma_f32_16x16x32_bf16 v[116:119], v[174:177], v[200:203], 0
	v_mfma_f32_16x16x32_bf16 v[112:115], v[182:185], v[200:203], 0
	v_mfma_f32_16x16x32_bf16 v[96:99], v[174:177], v[216:219], 0
	v_mfma_f32_16x16x32_bf16 v[100:103], v[182:185], v[216:219], 0
	v_mfma_f32_16x16x32_bf16 v[84:87], v[174:177], v[224:227], 0
	v_mfma_f32_16x16x32_bf16 v[80:83], v[182:185], v[224:227], 0
	v_mfma_f32_16x16x32_bf16 v[64:67], v[174:177], v[232:235], 0
	v_mfma_f32_16x16x32_bf16 v[68:71], v[182:185], v[232:235], 0
	v_mfma_f32_16x16x32_bf16 v[116:119], v[178:181], v[212:215], v[116:119]
	v_mfma_f32_16x16x32_bf16 v[112:115], v[196:199], v[212:215], v[112:115]
	v_mfma_f32_16x16x32_bf16 v[96:99], v[178:181], v[220:223], v[96:99]
	v_mfma_f32_16x16x32_bf16 v[100:103], v[196:199], v[220:223], v[100:103]
	v_mfma_f32_16x16x32_bf16 v[84:87], v[178:181], v[228:231], v[84:87]
	v_mfma_f32_16x16x32_bf16 v[80:83], v[196:199], v[228:231], v[80:83]
	v_mfma_f32_16x16x32_bf16 v[64:67], v[178:181], v[236:239], v[64:67]
	v_mfma_f32_16x16x32_bf16 v[68:71], v[196:199], v[236:239], v[68:71]
	s_setprio 0
	s_barrier
	ds_read_b128 v[200:203], v157 offset:16384
	ds_read_b128 v[212:215], v157 offset:17408
	ds_read_b128 v[216:219], v157 offset:18432
	ds_read_b128 v[220:223], v157 offset:19456
	ds_read_b128 v[224:227], v157 offset:20480
	ds_read_b128 v[228:231], v157 offset:21504
	ds_read_b128 v[232:235], v157 offset:22528
	ds_read_b128 v[236:239], v157 offset:23552
	s_add_u32 s96, s8, 0x40000
	s_addc_u32 s97, s9, 0
	s_add_u32 m0, s100, 0x10000
	s_nop 0
	global_load_lds_dwordx4 v128, s[8:9]
	s_add_u32 m0, s100, 0x12000
	s_nop 0
	global_load_lds_dwordx4 v130, s[8:9]
	s_add_u32 m0, s100, 0x14000
	s_nop 0
	global_load_lds_dwordx4 v128, s[96:97]
	s_add_u32 m0, s100, 0x16000
	s_nop 0
	global_load_lds_dwordx4 v130, s[96:97]
	s_mov_b32 m0, s100
	s_nop 0
	global_load_lds_dwordx4 v128, s[54:55]
	s_add_u32 m0, s100, 0x2000
	s_nop 0
	global_load_lds_dwordx4 v130, s[54:55]
	s_waitcnt vmcnt(8)
	s_waitcnt lgkmcnt(0)
	s_barrier
; #define WAIT_V(n) asm volatile("s_waitcnt vmcnt(" #n ")" ::: "memory")
; #define WAIT_L(n) asm volatile("s_waitcnt lgkmcnt(" #n ")" ::: "memory")
; #define BAR __builtin_amdgcn_s_barrier()
; #define SCHED __builtin_amdgcn_sched_barrier(0)
; #define STG_A(b, h, ptr) do { const char* _g = (ptr) + (h) * ahalf; LAS unsigned char* _l = lw + ((b) * 2 + (h)) * 16384; GLDS(_g + voa0, _l); GLDS(_g + voa1, _l + 8192); } while (0)
; #define STG_B(b, h, ptr) do { const char* _g = (ptr) + (h) * bhalf; LAS unsigned char* _l = lw + 65536 + ((b) * 2 + (h)) * 16384; GLDS(_g + vob0, _l); GLDS(_g + vob1, _l + 8192); } while (0)
; #define LDA(dst, b, h) _Pragma("unroll") for (int m = 0; m < 4; ++m) _Pragma("unroll") for (int k = 0; k < 2; ++k) dst[m][k] = *(const LAS bf16x8*)(la + ((b) * 2 + (h)) * 16384 + m * 2048 + k * 1024)
; #define LDB(dst, b, h) _Pragma("unroll") for (int n = 0; n < 2; ++n) _Pragma("unroll") for (int k = 0; k < 2; ++k) dst[n][k] = *(const LAS bf16x8*)(lb + ((b) * 2 + (h)) * 16384 + n * 2048 + k * 1024)
; #define MMA(ai, bj, Af, Bf) do { __builtin_amdgcn_s_setprio(1); \
;     _Pragma("unroll") for (int m = 0; m < 4; ++m) _Pragma("unroll") for (int n = 0; n < 2; ++n) _Pragma("unroll") for (int k = 0; k < 2; ++k) \
;         acc[ai][bj][m][n] = __builtin_amdgcn_mfma_f32_16x16x32_bf16(Bf[n][k], Af[m][k], acc[ai][bj][m][n], 0, 0, 0); \
;     __builtin_amdgcn_s_setprio(0); } while (0)
; template <int BMODE, class Epi, class TileFn>
; DEV void gemm_loop(LAS unsigned char* lds, const bf16_t* __restrict__ A, int lda, const bf16_t* __restrict__ B, int ldb, int K, const Epi& epi, int t0, int tstep, int tend, const TileFn& tf) {
;     ...
;             LDB(B0, 0, 0); LDB(B1, 0, 1); SCHED; LDA(At, 0, 0); STG_A(1, 1, a1);
;             WAIT_V(8); WAIT_L(0); BAR; MMA(0, 0, At, B0); MMA(0, 1, At, B1); BAR; SCHED;
;             LDA(At, 0, 1); STG_B(0, 0, b2); STG_B(0, 1, b2); STG_A(0, 0, a2);
;             WAIT_V(8); WAIT_L(0); BAR; MMA(1, 0, At, B0); MMA(1, 1, At, B1); BAR; SCHED;
	s_setprio 1
	s_waitcnt lgkmcnt(0)
	v_mfma_f32_16x16x32_bf16 v[60:63], v[158:161], v[200:203], 0
	v_mfma_f32_16x16x32_bf16 v[56:59], v[166:169], v[200:203], 0
	v_mfma_f32_16x16x32_bf16 v[40:43], v[158:161], v[216:219], 0
	v_mfma_f32_16x16x32_bf16 v[44:47], v[166:169], v[216:219], 0
	v_mfma_f32_16x16x32_bf16 v[28:31], v[158:161], v[224:227], 0
	v_mfma_f32_16x16x32_bf16 v[24:27], v[166:169], v[224:227], 0
	v_mfma_f32_16x16x32_bf16 v[8:11], v[158:161], v[232:235], 0
	v_mfma_f32_16x16x32_bf16 v[12:15], v[166:169], v[232:235], 0
	v_mfma_f32_16x16x32_bf16 v[60:63], v[162:165], v[212:215], v[60:63]
	v_mfma_f32_16x16x32_bf16 v[56:59], v[170:173], v[212:215], v[56:59]
	v_mfma_f32_16x16x32_bf16 v[40:43], v[162:165], v[220:223], v[40:43]
	v_mfma_f32_16x16x32_bf16 v[44:47], v[170:173], v[220:223], v[44:47]
	v_mfma_f32_16x16x32_bf16 v[28:31], v[162:165], v[228:231], v[28:31]
	v_mfma_f32_16x16x32_bf16 v[24:27], v[170:173], v[228:231], v[24:27]
	v_mfma_f32_16x16x32_bf16 v[8:11], v[162:165], v[236:239], v[8:11]
	v_mfma_f32_16x16x32_bf16 v[12:15], v[170:173], v[236:239], v[12:15]
	s_setprio 0
	s_setprio 1
	v_mfma_f32_16x16x32_bf16 v[52:55], v[174:177], v[200:203], 0
	v_mfma_f32_16x16x32_bf16 v[48:51], v[182:185], v[200:203], 0
	v_mfma_f32_16x16x32_bf16 v[32:35], v[174:177], v[216:219], 0
	v_mfma_f32_16x16x32_bf16 v[36:39], v[182:185], v[216:219], 0
	v_mfma_f32_16x16x32_bf16 v[20:23], v[174:177], v[224:227], 0
	v_mfma_f32_16x16x32_bf16 v[16:19], v[182:185], v[224:227], 0
	v_mfma_f32_16x16x32_bf16 v[0:3], v[174:177], v[232:235], 0
	v_mfma_f32_16x16x32_bf16 v[4:7], v[182:185], v[232:235], 0
	v_mfma_f32_16x16x32_bf16 v[52:55], v[178:181], v[212:215], v[52:55]
	v_mfma_f32_16x16x32_bf16 v[48:51], v[196:199], v[212:215], v[48:51]
	v_mfma_f32_16x16x32_bf16 v[32:35], v[178:181], v[220:223], v[32:35]
	v_mfma_f32_16x16x32_bf16 v[36:39], v[196:199], v[220:223], v[36:39]
	v_mfma_f32_16x16x32_bf16 v[20:23], v[178:181], v[228:231], v[20:23]
	v_mfma_f32_16x16x32_bf16 v[16:19], v[196:199], v[228:231], v[16:19]
	v_mfma_f32_16x16x32_bf16 v[0:3], v[178:181], v[236:239], v[0:3]
	v_mfma_f32_16x16x32_bf16 v[4:7], v[196:199], v[236:239], v[4:7]
	s_setprio 0
	s_barrier
	s_branch .Lkmid_1338
.LBB0_1338:
	ds_read_b128 v[158:161], v156
	ds_read_b128 v[162:165], v156 offset:1024
	ds_read_b128 v[166:169], v156 offset:2048
	ds_read_b128 v[170:173], v156 offset:3072
	ds_read_b128 v[174:177], v156 offset:16384
	ds_read_b128 v[178:181], v156 offset:17408
	ds_read_b128 v[182:185], v156 offset:18432
	ds_read_b128 v[196:199], v156 offset:19456
	s_add_u32 s8, s75, s36
	s_addc_u32 s9, s81, s37
	s_add_u32 s8, s8, 0x62e6100
	s_addc_u32 s9, s9, 0
	s_add_u32 s31, s92, s36
	s_addc_u32 s95, s93, s37
	s_cmpk_eq_i32 s36, 0x700
	s_cselect_b32 s55, s50, s9
	s_cselect_b32 s54, s30, s8
	s_cselect_b32 s9, s74, s95
	s_cselect_b32 s8, s53, s31
	v_lshl_add_u64 v[186:187], v[136:137], 0, s[36:37]
	v_lshl_add_u64 v[204:205], v[138:139], 0, s[36:37]
	s_add_u32 m0, s100, 0xc000
	ds_read_b128 v[200:203], v157
	ds_read_b128 v[212:215], v157 offset:1024
	ds_read_b128 v[216:219], v157 offset:2048
	ds_read_b128 v[220:223], v157 offset:3072
	ds_read_b128 v[224:227], v157 offset:4096
	ds_read_b128 v[228:231], v157 offset:5120
	ds_read_b128 v[232:235], v157 offset:6144
	ds_read_b128 v[236:239], v157 offset:7168
	global_load_lds_dwordx4 v[186:187], off
	s_add_u32 m0, s100, 0xe000
	s_nop 0
	global_load_lds_dwordx4 v[204:205], off
	s_waitcnt vmcnt(8)
	s_waitcnt lgkmcnt(0)
	s_barrier
	s_setprio 1
	s_waitcnt lgkmcnt(0)
	v_mfma_f32_16x16x32_bf16 v[124:127], v[158:161], v[200:203], v[124:127]
	v_mfma_f32_16x16x32_bf16 v[120:123], v[166:169], v[200:203], v[120:123]
	v_mfma_f32_16x16x32_bf16 v[104:107], v[158:161], v[216:219], v[104:107]
	v_mfma_f32_16x16x32_bf16 v[108:111], v[166:169], v[216:219], v[108:111]
	v_mfma_f32_16x16x32_bf16 v[92:95], v[158:161], v[224:227], v[92:95]
	v_mfma_f32_16x16x32_bf16 v[88:91], v[166:169], v[224:227], v[88:91]
	v_mfma_f32_16x16x32_bf16 v[72:75], v[158:161], v[232:235], v[72:75]
	v_mfma_f32_16x16x32_bf16 v[76:79], v[166:169], v[232:235], v[76:79]
	v_mfma_f32_16x16x32_bf16 v[124:127], v[162:165], v[212:215], v[124:127]
	v_mfma_f32_16x16x32_bf16 v[120:123], v[170:173], v[212:215], v[120:123]
	v_mfma_f32_16x16x32_bf16 v[104:107], v[162:165], v[220:223], v[104:107]
	v_mfma_f32_16x16x32_bf16 v[108:111], v[170:173], v[220:223], v[108:111]
	v_mfma_f32_16x16x32_bf16 v[92:95], v[162:165], v[228:231], v[92:95]
	v_mfma_f32_16x16x32_bf16 v[88:91], v[170:173], v[228:231], v[88:91]
	v_mfma_f32_16x16x32_bf16 v[72:75], v[162:165], v[236:239], v[72:75]
	v_mfma_f32_16x16x32_bf16 v[76:79], v[170:173], v[236:239], v[76:79]
	s_setprio 0
	s_setprio 1
	v_mfma_f32_16x16x32_bf16 v[116:119], v[174:177], v[200:203], v[116:119]
	v_mfma_f32_16x16x32_bf16 v[112:115], v[182:185], v[200:203], v[112:115]
	v_mfma_f32_16x16x32_bf16 v[96:99], v[174:177], v[216:219], v[96:99]
	v_mfma_f32_16x16x32_bf16 v[100:103], v[182:185], v[216:219], v[100:103]
	v_mfma_f32_16x16x32_bf16 v[84:87], v[174:177], v[224:227], v[84:87]
	v_mfma_f32_16x16x32_bf16 v[80:83], v[182:185], v[224:227], v[80:83]
	v_mfma_f32_16x16x32_bf16 v[64:67], v[174:177], v[232:235], v[64:67]
	v_mfma_f32_16x16x32_bf16 v[68:71], v[182:185], v[232:235], v[68:71]
	v_mfma_f32_16x16x32_bf16 v[116:119], v[178:181], v[212:215], v[116:119]
	v_mfma_f32_16x16x32_bf16 v[112:115], v[196:199], v[212:215], v[112:115]
	v_mfma_f32_16x16x32_bf16 v[96:99], v[178:181], v[220:223], v[96:99]
	v_mfma_f32_16x16x32_bf16 v[100:103], v[196:199], v[220:223], v[100:103]
	v_mfma_f32_16x16x32_bf16 v[84:87], v[178:181], v[228:231], v[84:87]
	v_mfma_f32_16x16x32_bf16 v[80:83], v[196:199], v[228:231], v[80:83]
	v_mfma_f32_16x16x32_bf16 v[64:67], v[178:181], v[236:239], v[64:67]
	v_mfma_f32_16x16x32_bf16 v[68:71], v[196:199], v[236:239], v[68:71]
	s_setprio 0
	s_barrier
; #define WAIT_V(n) asm volatile("s_waitcnt vmcnt(" #n ")" ::: "memory")
; #define WAIT_L(n) asm volatile("s_waitcnt lgkmcnt(" #n ")" ::: "memory")
; #define BAR __builtin_amdgcn_s_barrier()
; #define SCHED __builtin_amdgcn_sched_barrier(0)
; #define STG_A(b, h, ptr) do { const char* _g = (ptr) + (h) * ahalf; LAS unsigned char* _l = lw + ((b) * 2 + (h)) * 16384; GLDS(_g + voa0, _l); GLDS(_g + voa1, _l + 8192); } while (0)
; #define STG_B(b, h, ptr) do { const char* _g = (ptr) + (h) * bhalf; LAS unsigned char* _l = lw + 65536 + ((b) * 2 + (h)) * 16384; GLDS(_g + vob0, _l); GLDS(_g + vob1, _l + 8192); } while (0)
; #define LDA(dst, b, h) _Pragma("unroll") for (int m = 0; m < 4; ++m) _Pragma("unroll") for (int k = 0; k < 2; ++k) dst[m][k] = *(const LAS bf16x8*)(la + ((b) * 2 + (h)) * 16384 + m * 2048 + k * 1024)
; #define MMA(ai, bj, Af, Bf) do { __builtin_amdgcn_s_setprio(1); \
;     _Pragma("unroll") for (int m = 0; m < 4; ++m) _Pragma("unroll") for (int n = 0; n < 2; ++n) _Pragma("unroll") for (int k = 0; k < 2; ++k) \
;         acc[ai][bj][m][n] = __builtin_amdgcn_mfma_f32_16x16x32_bf16(Bf[n][k], Af[m][k], acc[ai][bj][m][n], 0, 0, 0); \
;     __builtin_amdgcn_s_setprio(0); } while (0)
; template <int BMODE, class Epi, class TileFn>
; DEV void gemm_loop(LAS unsigned char* lds, const bf16_t* __restrict__ A, int lda, const bf16_t* __restrict__ B, int ldb, int K, const Epi& epi, int t0, int tstep, int tend, const TileFn& tf) {
;     ...
;             LDA(At, 0, 1); STG_B(0, 0, b2); STG_B(0, 1, b2); STG_A(0, 0, a2);
;             WAIT_V(8); WAIT_L(0); BAR; MMA(1, 0, At, B0); MMA(1, 1, At, B1); BAR; SCHED;
	ds_read_b128 v[200:203], v157 offset:16384
	ds_read_b128 v[212:215], v157 offset:17408
	ds_read_b128 v[216:219], v157 offset:18432
	ds_read_b128 v[220:223], v157 offset:19456
	ds_read_b128 v[224:227], v157 offset:20480
	ds_read_b128 v[228:231], v157 offset:21504
	ds_read_b128 v[232:235], v157 offset:22528
	ds_read_b128 v[236:239], v157 offset:23552
	s_add_u32 s96, s8, 0x40000
	s_addc_u32 s97, s9, 0
	s_add_u32 m0, s100, 0x10000
	s_nop 0
	global_load_lds_dwordx4 v128, s[8:9]
	s_add_u32 m0, s100, 0x12000
	s_nop 0
	global_load_lds_dwordx4 v130, s[8:9]
	s_add_u32 m0, s100, 0x14000
	s_nop 0
	global_load_lds_dwordx4 v128, s[96:97]
	s_add_u32 m0, s100, 0x16000
	s_nop 0
	global_load_lds_dwordx4 v130, s[96:97]
	s_mov_b32 m0, s100
	s_nop 0
	global_load_lds_dwordx4 v128, s[54:55]
	s_add_u32 m0, s100, 0x2000
	s_nop 0
	global_load_lds_dwordx4 v130, s[54:55]
	s_waitcnt vmcnt(8)
	s_waitcnt lgkmcnt(0)
	s_barrier
	s_setprio 1
	s_waitcnt lgkmcnt(0)
	v_mfma_f32_16x16x32_bf16 v[60:63], v[158:161], v[200:203], v[60:63]
	v_mfma_f32_16x16x32_bf16 v[56:59], v[166:169], v[200:203], v[56:59]
	v_mfma_f32_16x16x32_bf16 v[40:43], v[158:161], v[216:219], v[40:43]
	v_mfma_f32_16x16x32_bf16 v[44:47], v[166:169], v[216:219], v[44:47]
	v_mfma_f32_16x16x32_bf16 v[28:31], v[158:161], v[224:227], v[28:31]
	v_mfma_f32_16x16x32_bf16 v[24:27], v[166:169], v[224:227], v[24:27]
	v_mfma_f32_16x16x32_bf16 v[8:11], v[158:161], v[232:235], v[8:11]
	v_mfma_f32_16x16x32_bf16 v[12:15], v[166:169], v[232:235], v[12:15]
	v_mfma_f32_16x16x32_bf16 v[60:63], v[162:165], v[212:215], v[60:63]
	v_mfma_f32_16x16x32_bf16 v[56:59], v[170:173], v[212:215], v[56:59]
	v_mfma_f32_16x16x32_bf16 v[40:43], v[162:165], v[220:223], v[40:43]
	v_mfma_f32_16x16x32_bf16 v[44:47], v[170:173], v[220:223], v[44:47]
	v_mfma_f32_16x16x32_bf16 v[28:31], v[162:165], v[228:231], v[28:31]
	v_mfma_f32_16x16x32_bf16 v[24:27], v[170:173], v[228:231], v[24:27]
	v_mfma_f32_16x16x32_bf16 v[8:11], v[162:165], v[236:239], v[8:11]
	v_mfma_f32_16x16x32_bf16 v[12:15], v[170:173], v[236:239], v[12:15]
	s_setprio 0
	s_setprio 1
	v_mfma_f32_16x16x32_bf16 v[52:55], v[174:177], v[200:203], v[52:55]
	v_mfma_f32_16x16x32_bf16 v[48:51], v[182:185], v[200:203], v[48:51]
	v_mfma_f32_16x16x32_bf16 v[32:35], v[174:177], v[216:219], v[32:35]
	v_mfma_f32_16x16x32_bf16 v[36:39], v[182:185], v[216:219], v[36:39]
	v_mfma_f32_16x16x32_bf16 v[20:23], v[174:177], v[224:227], v[20:23]
	v_mfma_f32_16x16x32_bf16 v[16:19], v[182:185], v[224:227], v[16:19]
	v_mfma_f32_16x16x32_bf16 v[0:3], v[174:177], v[232:235], v[0:3]
	v_mfma_f32_16x16x32_bf16 v[4:7], v[182:185], v[232:235], v[4:7]
	v_mfma_f32_16x16x32_bf16 v[52:55], v[178:181], v[212:215], v[52:55]
	v_mfma_f32_16x16x32_bf16 v[48:51], v[196:199], v[212:215], v[48:51]
	v_mfma_f32_16x16x32_bf16 v[32:35], v[178:181], v[220:223], v[32:35]
	v_mfma_f32_16x16x32_bf16 v[36:39], v[196:199], v[220:223], v[36:39]
	v_mfma_f32_16x16x32_bf16 v[20:23], v[178:181], v[228:231], v[20:23]
	v_mfma_f32_16x16x32_bf16 v[16:19], v[196:199], v[228:231], v[16:19]
	v_mfma_f32_16x16x32_bf16 v[0:3], v[178:181], v[236:239], v[0:3]
	v_mfma_f32_16x16x32_bf16 v[4:7], v[196:199], v[236:239], v[4:7]
	s_setprio 0
	s_barrier
; #define WAIT_V(n) asm volatile("s_waitcnt vmcnt(" #n ")" ::: "memory")
; #define WAIT_L(n) asm volatile("s_waitcnt lgkmcnt(" #n ")" ::: "memory")
; #define BAR __builtin_amdgcn_s_barrier()
; #define SCHED __builtin_amdgcn_sched_barrier(0)
; #define STG_A(b, h, ptr) do { const char* _g = (ptr) + (h) * ahalf; LAS unsigned char* _l = lw + ((b) * 2 + (h)) * 16384; GLDS(_g + voa0, _l); GLDS(_g + voa1, _l + 8192); } while (0)
; #define STG_B(b, h, ptr) do { const char* _g = (ptr) + (h) * bhalf; LAS unsigned char* _l = lw + 65536 + ((b) * 2 + (h)) * 16384; GLDS(_g + vob0, _l); GLDS(_g + vob1, _l + 8192); } while (0)
; #define LDA(dst, b, h) _Pragma("unroll") for (int m = 0; m < 4; ++m) _Pragma("unroll") for (int k = 0; k < 2; ++k) dst[m][k] = *(const LAS bf16x8*)(la + ((b) * 2 + (h)) * 16384 + m * 2048 + k * 1024)
; #define LDB(dst, b, h) _Pragma("unroll") for (int n = 0; n < 2; ++n) _Pragma("unroll") for (int k = 0; k < 2; ++k) dst[n][k] = *(const LAS bf16x8*)(lb + ((b) * 2 + (h)) * 16384 + n * 2048 + k * 1024)
; #define MMA(ai, bj, Af, Bf) do { __builtin_amdgcn_s_setprio(1); \
;     _Pragma("unroll") for (int m = 0; m < 4; ++m) _Pragma("unroll") for (int n = 0; n < 2; ++n) _Pragma("unroll") for (int k = 0; k < 2; ++k) \
;         acc[ai][bj][m][n] = __builtin_amdgcn_mfma_f32_16x16x32_bf16(Bf[n][k], Af[m][k], acc[ai][bj][m][n], 0, 0, 0); \
;     __builtin_amdgcn_s_setprio(0); } while (0)
; template <int BMODE, class Epi, class TileFn>
; DEV void gemm_loop(LAS unsigned char* lds, const bf16_t* __restrict__ A, int lda, const bf16_t* __restrict__ B, int ldb, int K, const Epi& epi, int t0, int tstep, int tend, const TileFn& tf) {
;     ...
;             LDB(B0, 1, 0); LDB(B1, 1, 1); SCHED; LDA(At, 1, 0); STG_A(0, 1, a2);
;             WAIT_V(8); WAIT_L(0); BAR; MMA(0, 0, At, B0); MMA(0, 1, At, B1); BAR; SCHED;
;             LDA(At, 1, 1); STG_B(1, 0, b3); STG_B(1, 1, b3); STG_A(1, 0, a3);
;             WAIT_V(8); WAIT_L(0); BAR; MMA(1, 0, At, B0); MMA(1, 1, At, B1); BAR; SCHED;
;         }
.Lkmid_1338:
	ds_read_b128 v[158:161], v156 offset:32768
	ds_read_b128 v[162:165], v156 offset:33792
	ds_read_b128 v[166:169], v156 offset:34816
	ds_read_b128 v[170:173], v156 offset:35840
	ds_read_b128 v[174:177], v156 offset:49152
	ds_read_b128 v[178:181], v156 offset:50176
	ds_read_b128 v[182:185], v156 offset:51200
	ds_read_b128 v[196:199], v156 offset:52224
	ds_read_b128 v[200:203], v157 offset:32768
	ds_read_b128 v[212:215], v157 offset:33792
	ds_read_b128 v[216:219], v157 offset:34816
	ds_read_b128 v[220:223], v157 offset:35840
	ds_read_b128 v[224:227], v157 offset:36864
	ds_read_b128 v[228:231], v157 offset:37888
	ds_read_b128 v[232:235], v157 offset:38912
	ds_read_b128 v[236:239], v157 offset:39936
	s_add_u32 s54, s54, 0x40000
	s_addc_u32 s55, s55, 0
	s_add_u32 m0, s100, 0x4000
	s_nop 0
	global_load_lds_dwordx4 v128, s[54:55]
	s_add_u32 m0, s100, 0x6000
	s_nop 0
	global_load_lds_dwordx4 v130, s[54:55]
	s_waitcnt vmcnt(8)
	s_waitcnt lgkmcnt(0)
	s_barrier
	s_setprio 1
	s_waitcnt lgkmcnt(0)
	v_mfma_f32_16x16x32_bf16 v[124:127], v[158:161], v[200:203], v[124:127]
	v_mfma_f32_16x16x32_bf16 v[120:123], v[166:169], v[200:203], v[120:123]
	v_mfma_f32_16x16x32_bf16 v[104:107], v[158:161], v[216:219], v[104:107]
	v_mfma_f32_16x16x32_bf16 v[108:111], v[166:169], v[216:219], v[108:111]
	v_mfma_f32_16x16x32_bf16 v[92:95], v[158:161], v[224:227], v[92:95]
	v_mfma_f32_16x16x32_bf16 v[88:91], v[166:169], v[224:227], v[88:91]
	v_mfma_f32_16x16x32_bf16 v[72:75], v[158:161], v[232:235], v[72:75]
	v_mfma_f32_16x16x32_bf16 v[76:79], v[166:169], v[232:235], v[76:79]
	v_mfma_f32_16x16x32_bf16 v[124:127], v[162:165], v[212:215], v[124:127]
	v_mfma_f32_16x16x32_bf16 v[120:123], v[170:173], v[212:215], v[120:123]
	v_mfma_f32_16x16x32_bf16 v[104:107], v[162:165], v[220:223], v[104:107]
	v_mfma_f32_16x16x32_bf16 v[108:111], v[170:173], v[220:223], v[108:111]
	v_mfma_f32_16x16x32_bf16 v[92:95], v[162:165], v[228:231], v[92:95]
	v_mfma_f32_16x16x32_bf16 v[88:91], v[170:173], v[228:231], v[88:91]
	v_mfma_f32_16x16x32_bf16 v[72:75], v[162:165], v[236:239], v[72:75]
	v_mfma_f32_16x16x32_bf16 v[76:79], v[170:173], v[236:239], v[76:79]
	s_setprio 0
	s_setprio 1
	v_mfma_f32_16x16x32_bf16 v[116:119], v[174:177], v[200:203], v[116:119]
	v_mfma_f32_16x16x32_bf16 v[112:115], v[182:185], v[200:203], v[112:115]
	v_mfma_f32_16x16x32_bf16 v[96:99], v[174:177], v[216:219], v[96:99]
	v_mfma_f32_16x16x32_bf16 v[100:103], v[182:185], v[216:219], v[100:103]
	v_mfma_f32_16x16x32_bf16 v[84:87], v[174:177], v[224:227], v[84:87]
	v_mfma_f32_16x16x32_bf16 v[80:83], v[182:185], v[224:227], v[80:83]
	v_mfma_f32_16x16x32_bf16 v[64:67], v[174:177], v[232:235], v[64:67]
	v_mfma_f32_16x16x32_bf16 v[68:71], v[182:185], v[232:235], v[68:71]
	v_mfma_f32_16x16x32_bf16 v[116:119], v[178:181], v[212:215], v[116:119]
	v_mfma_f32_16x16x32_bf16 v[112:115], v[196:199], v[212:215], v[112:115]
	v_mfma_f32_16x16x32_bf16 v[96:99], v[178:181], v[220:223], v[96:99]
	v_mfma_f32_16x16x32_bf16 v[100:103], v[196:199], v[220:223], v[100:103]
	v_mfma_f32_16x16x32_bf16 v[84:87], v[178:181], v[228:231], v[84:87]
	v_mfma_f32_16x16x32_bf16 v[80:83], v[196:199], v[228:231], v[80:83]
	v_mfma_f32_16x16x32_bf16 v[64:67], v[178:181], v[236:239], v[64:67]
	v_mfma_f32_16x16x32_bf16 v[68:71], v[196:199], v[236:239], v[68:71]
	s_setprio 0
	s_barrier
	ds_read_b128 v[200:203], v157 offset:49152
	ds_read_b128 v[212:215], v157 offset:50176
	ds_read_b128 v[216:219], v157 offset:51200
	ds_read_b128 v[220:223], v157 offset:52224
	ds_read_b128 v[224:227], v157 offset:53248
	ds_read_b128 v[228:231], v157 offset:54272
	ds_read_b128 v[232:235], v157 offset:55296
	ds_read_b128 v[236:239], v157 offset:56320
	s_add_u32 s8, s8, s2
	s_addc_u32 s9, s9, s3
	s_add_u32 m0, s100, 0x18000
	s_nop 0
	global_load_lds_dwordx4 v128, s[8:9]
	s_add_u32 m0, s100, 0x1a000
	s_nop 0
	global_load_lds_dwordx4 v130, s[8:9]
	s_add_u32 s8, s8, 0x40000
	s_addc_u32 s9, s9, 0
	s_add_u32 m0, s100, 0x1c000
	s_nop 0
	global_load_lds_dwordx4 v128, s[8:9]
	s_add_u32 m0, s100, 0x1e000
	s_nop 0
	global_load_lds_dwordx4 v130, s[8:9]
	s_sub_u32 s96, s54, 0x40000
	s_subb_u32 s97, s55, 0
	s_add_u32 s96, s96, s2
	s_addc_u32 s97, s97, s3
	s_add_u32 m0, s100, 0x8000
	s_nop 0
	global_load_lds_dwordx4 v128, s[96:97]
	s_add_u32 m0, s100, 0xa000
	s_nop 0
	global_load_lds_dwordx4 v130, s[96:97]
	s_waitcnt vmcnt(8)
	s_waitcnt lgkmcnt(0)
	s_barrier
	s_setprio 1
	s_waitcnt lgkmcnt(0)
	v_mfma_f32_16x16x32_bf16 v[60:63], v[158:161], v[200:203], v[60:63]
	v_mfma_f32_16x16x32_bf16 v[56:59], v[166:169], v[200:203], v[56:59]
	v_mfma_f32_16x16x32_bf16 v[40:43], v[158:161], v[216:219], v[40:43]
	v_mfma_f32_16x16x32_bf16 v[44:47], v[166:169], v[216:219], v[44:47]
	v_mfma_f32_16x16x32_bf16 v[28:31], v[158:161], v[224:227], v[28:31]
	v_mfma_f32_16x16x32_bf16 v[24:27], v[166:169], v[224:227], v[24:27]
	v_mfma_f32_16x16x32_bf16 v[8:11], v[158:161], v[232:235], v[8:11]
	v_mfma_f32_16x16x32_bf16 v[12:15], v[166:169], v[232:235], v[12:15]
	v_mfma_f32_16x16x32_bf16 v[60:63], v[162:165], v[212:215], v[60:63]
	v_mfma_f32_16x16x32_bf16 v[56:59], v[170:173], v[212:215], v[56:59]
	v_mfma_f32_16x16x32_bf16 v[40:43], v[162:165], v[220:223], v[40:43]
	v_mfma_f32_16x16x32_bf16 v[44:47], v[170:173], v[220:223], v[44:47]
	v_mfma_f32_16x16x32_bf16 v[28:31], v[162:165], v[228:231], v[28:31]
	v_mfma_f32_16x16x32_bf16 v[24:27], v[170:173], v[228:231], v[24:27]
	v_mfma_f32_16x16x32_bf16 v[8:11], v[162:165], v[236:239], v[8:11]
	v_mfma_f32_16x16x32_bf16 v[12:15], v[170:173], v[236:239], v[12:15]
	s_setprio 0
	s_setprio 1
	v_mfma_f32_16x16x32_bf16 v[52:55], v[174:177], v[200:203], v[52:55]
	v_mfma_f32_16x16x32_bf16 v[48:51], v[182:185], v[200:203], v[48:51]
	v_mfma_f32_16x16x32_bf16 v[32:35], v[174:177], v[216:219], v[32:35]
	v_mfma_f32_16x16x32_bf16 v[36:39], v[182:185], v[216:219], v[36:39]
	v_mfma_f32_16x16x32_bf16 v[20:23], v[174:177], v[224:227], v[20:23]
	v_mfma_f32_16x16x32_bf16 v[16:19], v[182:185], v[224:227], v[16:19]
	v_mfma_f32_16x16x32_bf16 v[0:3], v[174:177], v[232:235], v[0:3]
	v_mfma_f32_16x16x32_bf16 v[4:7], v[182:185], v[232:235], v[4:7]
	v_mfma_f32_16x16x32_bf16 v[52:55], v[178:181], v[212:215], v[52:55]
	v_mfma_f32_16x16x32_bf16 v[48:51], v[196:199], v[212:215], v[48:51]
	v_mfma_f32_16x16x32_bf16 v[32:35], v[178:181], v[220:223], v[32:35]
	v_mfma_f32_16x16x32_bf16 v[36:39], v[196:199], v[220:223], v[36:39]
	v_mfma_f32_16x16x32_bf16 v[20:23], v[178:181], v[228:231], v[20:23]
	v_mfma_f32_16x16x32_bf16 v[16:19], v[196:199], v[228:231], v[16:19]
	v_mfma_f32_16x16x32_bf16 v[0:3], v[178:181], v[236:239], v[0:3]
	v_mfma_f32_16x16x32_bf16 v[4:7], v[196:199], v[236:239], v[4:7]
	s_setprio 0
	s_barrier
	s_add_i32 s94, s94, 2
	s_add_u32 s36, s36, 0x100
	s_addc_u32 s37, s37, 0
	s_cmp_gt_u32 s94, 13
	s_cbranch_scc0 .LBB0_1338
	s_and_saveexec_b64 s[8:9], s[44:45]
	s_cbranch_execz .LBB0_1341
	s_barrier

; #define LAS __attribute__((address_space(3)))
; __global__ void __launch_bounds__(NT, 2) fwd_mega(Params p) {
;     extern __shared__ __attribute__((aligned(16))) unsigned char lds_raw[];
;     LAS unsigned char* lds = (LAS unsigned char*)lds_raw;
	.amdhsa_kernel _Z8fwd_mega6Params
		.amdhsa_group_segment_fixed_size 0
		.amdhsa_private_segment_fixed_size 0
		.amdhsa_kernarg_size 384
		.amdhsa_user_sgpr_count 2
		.amdhsa_user_sgpr_dispatch_ptr 0
		.amdhsa_user_sgpr_queue_ptr 0
		.amdhsa_user_sgpr_kernarg_segment_ptr 1
		.amdhsa_user_sgpr_dispatch_id 0
		.amdhsa_user_sgpr_kernarg_preload_length 0
		.amdhsa_user_sgpr_kernarg_preload_offset 0
		.amdhsa_user_sgpr_private_segment_size 0
		.amdhsa_uses_dynamic_stack 0
		.amdhsa_enable_private_segment 0
		.amdhsa_system_sgpr_workgroup_id_x 1
		.amdhsa_system_sgpr_workgroup_id_y 0
		.amdhsa_system_sgpr_workgroup_id_z 0
		.amdhsa_system_sgpr_workgroup_info 0
		.amdhsa_system_vgpr_workitem_id 2
		.amdhsa_next_free_vgpr 255
		.amdhsa_next_free_sgpr 102
		.amdhsa_accum_offset 256
		.amdhsa_reserve_vcc 1
		.amdhsa_float_round_mode_32 0
		.amdhsa_float_round_mode_16_64 0
		.amdhsa_float_denorm_mode_32 3
		.amdhsa_float_denorm_mode_16_64 3
		.amdhsa_dx10_clamp 1
		.amdhsa_ieee_mode 1
		.amdhsa_fp16_overflow 0
		.amdhsa_tg_split 0
		.amdhsa_exception_fp_ieee_invalid_op 0
		.amdhsa_exception_fp_denorm_src 0
		.amdhsa_exception_fp_ieee_div_zero 0
		.amdhsa_exception_fp_ieee_overflow 0
		.amdhsa_exception_fp_ieee_underflow 0
		.amdhsa_exception_fp_ieee_inexact 0
		.amdhsa_exception_int_div_zero 0
	.end_amdhsa_kernel

; #define LAS __attribute__((address_space(3)))
; __global__ void __launch_bounds__(NT, 2) fwd_mega(Params p) {
;     extern __shared__ __attribute__((aligned(16))) unsigned char lds_raw[];
;     LAS unsigned char* lds = (LAS unsigned char*)lds_raw;
amdhsa.kernels:
  - .agpr_count:     0
    .args:
      - .offset:         0
        .size:           128
        .value_kind:     by_value
      - .offset:         128
        .size:           4
        .value_kind:     hidden_block_count_x
      - .offset:         132
        .size:           4
        .value_kind:     hidden_block_count_y
      - .offset:         136
        .size:           4
        .value_kind:     hidden_block_count_z
      - .offset:         140
        .size:           2
        .value_kind:     hidden_group_size_x
      - .offset:         142
        .size:           2
        .value_kind:     hidden_group_size_y
      - .offset:         144
        .size:           2
        .value_kind:     hidden_group_size_z
      - .offset:         146
        .size:           2
        .value_kind:     hidden_remainder_x
      - .offset:         148
        .size:           2
        .value_kind:     hidden_remainder_y
      - .offset:         150
        .size:           2
        .value_kind:     hidden_remainder_z
      - .offset:         168
        .size:           8
        .value_kind:     hidden_global_offset_x
      - .offset:         176
        .size:           8
        .value_kind:     hidden_global_offset_y
      - .offset:         184
        .size:           8
        .value_kind:     hidden_global_offset_z
      - .offset:         192
        .size:           2
        .value_kind:     hidden_grid_dims
      - .offset:         216
        .size:           8
        .value_kind:     hidden_multigrid_sync_arg
      - .offset:         248
        .size:           4
        .value_kind:     hidden_dynamic_lds_size
    .group_segment_fixed_size: 0
    .kernarg_segment_align: 8
    .kernarg_segment_size: 384
    .language:       OpenCL C
    .language_version:
      - 2
      - 0
    .max_flat_workgroup_size: 512
    .name:           _Z8fwd_mega6Params
    .private_segment_fixed_size: 0
    .sgpr_count:     108
    .sgpr_spill_count: 300
    .symbol:         _Z8fwd_mega6Params.kd
    .uniform_work_group_size: 1
    .uses_dynamic_stack: false
    .vgpr_count:     255
    .vgpr_spill_count: 0
    .wavefront_size: 64
